# ps1 + code placement: one 4-byte pad after barrier 2 so the P2 hot loop heads return to 0 mod 8 byte offsets
# baseline (speedup 1.0000x reference)
; __global__ void __launch_bounds__(NWAVES * 64, LBW) fwd_kernel(Args A) {
;     ...
;         if (wave == 0) {
;             const float a = wave_sum(A.lq1[lane] * A.lk1[lane]), c = wave_sum(A.lq2[lane] * A.lk2[lane]);
;             if (lane == 0) misc[4] = expf(a) - expf(c) + 0.2f;
.LBB0_257:
	s_nop 0
	s_or_b64 exec, exec, s[2:3]
	s_cmp_lt_u32 s33, 64
	s_cselect_b64 s[2:3], -1, 0
	s_cmp_gt_u32 s33, 63
	v_cmp_eq_u32_e32 vcc, 0, v194
	s_waitcnt lgkmcnt(0)
	s_barrier
	s_cbranch_scc1 .LBB0_261
	global_load_dword v1, v196, s[56:57]
	global_load_dword v2, v196, s[58:59]
	global_load_dword v3, v196, s[60:61]
	global_load_dword v4, v196, s[62:63]
	s_waitcnt vmcnt(2)
	v_mul_f32_e32 v5, v1, v2
	s_nop 1
	v_mov_b32_dpp v5, v5 quad_perm:[1,0,3,2] row_mask:0xf bank_mask:0xf bound_ctrl:1
	s_waitcnt vmcnt(0)
	v_mul_f32_e32 v6, v3, v4
	v_fmac_f32_e32 v5, v1, v2
	s_nop 0
	v_mov_b32_dpp v6, v6 quad_perm:[1,0,3,2] row_mask:0xf bank_mask:0xf bound_ctrl:1
	v_fmac_f32_e32 v6, v3, v4
	v_add_f32_dpp v1, v5, v5 quad_perm:[2,3,0,1] row_mask:0xf bank_mask:0xf bound_ctrl:1
	s_nop 0
	v_add_f32_dpp v2, v6, v6 quad_perm:[2,3,0,1] row_mask:0xf bank_mask:0xf bound_ctrl:1
	v_add_f32_dpp v1, v1, v1 row_half_mirror row_mask:0xf bank_mask:0xf bound_ctrl:1
	s_nop 0
	v_add_f32_dpp v2, v2, v2 row_half_mirror row_mask:0xf bank_mask:0xf bound_ctrl:1
	v_add_f32_dpp v1, v1, v1 row_mirror row_mask:0xf bank_mask:0xf bound_ctrl:1
	v_mov_b32_e32 v3, v1
	v_add_f32_dpp v2, v2, v2 row_mirror row_mask:0xf bank_mask:0xf bound_ctrl:1
	v_mov_b32_e32 v4, v2
	v_permlane16_swap_b32_e32 v1, v3
	s_nop 0
	v_permlane16_swap_b32_e32 v2, v4
	v_add_f32_e32 v3, v1, v3
	v_add_f32_e32 v1, v2, v4
	v_mov_b32_e32 v4, v3
	v_mov_b32_e32 v2, v1
	s_nop 0
	v_permlane32_swap_b32_e32 v3, v4
	v_permlane32_swap_b32_e32 v1, v2
	s_and_saveexec_b64 s[4:5], vcc
	s_cbranch_execz .LBB0_260
	v_add_f32_e32 v3, v3, v4
	s_mov_b32 s0, 0x3fb8aa3b
	v_mul_f32_e32 v4, 0x3fb8aa3b, v3
	v_fma_f32 v5, v3, s0, -v4
	v_rndne_f32_e32 v6, v4
	v_fmac_f32_e32 v5, 0x32a5705f, v3
	v_sub_f32_e32 v4, v4, v6
	v_add_f32_e32 v4, v4, v5
	v_exp_f32_e32 v4, v4
	v_cvt_i32_f32_e32 v5, v6
	v_add_f32_e32 v1, v1, v2
	v_mul_f32_e32 v2, 0x3fb8aa3b, v1
	v_rndne_f32_e32 v6, v2
	v_ldexp_f32 v4, v4, v5
	v_fma_f32 v5, v1, s0, -v2
	v_fmac_f32_e32 v5, 0x32a5705f, v1
	v_sub_f32_e32 v2, v2, v6
	v_add_f32_e32 v2, v2, v5
	v_exp_f32_e32 v2, v2
	v_cvt_i32_f32_e32 v5, v6
	s_mov_b32 s1, 0xc2ce8ed0
	v_cmp_ngt_f32_e32 vcc, s1, v3
	s_mov_b32 s6, 0x42b17218
	v_mov_b32_e32 v6, 0x7f800000
	v_cndmask_b32_e32 v4, 0, v4, vcc
	v_cmp_nlt_f32_e32 vcc, s6, v3
	v_ldexp_f32 v2, v2, v5
	s_add_i32 s0, 0, 0x21010
	v_cndmask_b32_e32 v3, v6, v4, vcc
	v_cmp_ngt_f32_e32 vcc, s1, v1
	s_nop 1
	v_cndmask_b32_e32 v2, 0, v2, vcc
	v_cmp_nlt_f32_e32 vcc, s6, v1
	s_nop 1
	v_cndmask_b32_e32 v1, v6, v2, vcc
	v_sub_f32_e32 v1, v3, v1
	v_add_f32_e32 v1, 0x3e4ccccd, v1
	v_mov_b32_e32 v2, s0
	ds_write_b32 v2, v1
